# two-level fast grid barrier (per-XCD arrive + global counter poll) replacing barriers after phases 1..21; fixes leader-lane register for barriers after hand-written P3/P19
# speedup vs baseline: 1.1280x; 1.0024x over previous
.LBB0_241:
	s_cmp_lt_i32 s45, 3
	s_cbranch_scc1 .LBB0_295
	s_waitcnt vmcnt(0) lgkmcnt(0)
	s_barrier
	v_mbcnt_hi_u32_b32 v0, -1, v210
	v_cmp_eq_u32_e32 vcc, 0, v0
	s_and_b64 s[4:5], s[46:47], vcc
	s_and_saveexec_b64 s[2:3], s[4:5]
	s_cbranch_execz .Lfb1_join
	v_mov_b32_e32 v0, 0x24400
	ds_read_b32 v1, v0
	ds_read_b32 v2, v0 offset:4
	ds_read_b32 v3, v0 offset:8
	s_waitcnt lgkmcnt(0)
	v_readfirstlane_b32 s4, v1
	v_readfirstlane_b32 s5, v2
	v_readfirstlane_b32 s6, v3
	s_add_u32 s7, s6, 1
	v_mov_b32_e32 v4, s7
	ds_write_b32 v0, v4 offset:8
	s_mul_i32 s8, s7, s4
	s_mul_i32 s9, s7, s5
	s_lshl_b32 s10, s23, 7
	s_add_u32 s10, s10, 0x3600
	v_mov_b32_e32 v1, s10
	v_mov_b32_e32 v2, 1
	global_atomic_add v3, v1, v2, s[40:41] sc0
	s_waitcnt vmcnt(0)
	v_readfirstlane_b32 s11, v3
	s_add_u32 s11, s11, 1
	v_mov_b32_e32 v1, 0x3e00
	s_cmp_lg_u32 s11, s8
	s_cbranch_scc1 .Lfb1_spin
	buffer_wbl2 sc1
	s_waitcnt vmcnt(0)
	global_atomic_add v1, v2, s[40:41]
.Lfb1_spin:
	global_load_dword v3, v1, s[40:41] sc1
	s_waitcnt vmcnt(0)
	v_readfirstlane_b32 s11, v3
	s_cmp_ge_u32 s11, s9
	s_cbranch_scc1 .Lfb1_acq
	s_sleep 1
	s_branch .Lfb1_spin

.Lfb1_join:
	s_or_b64 exec, exec, s[2:3]
	s_waitcnt vmcnt(0) lgkmcnt(0)
	s_barrier

.LBB0_811:
	s_cmp_lt_i32 s45, 4
	s_cbranch_scc1 .LBB0_865
	s_waitcnt vmcnt(0) lgkmcnt(0)
	s_barrier
	v_mbcnt_hi_u32_b32 v0, -1, v210
	v_cmp_eq_u32_e32 vcc, 0, v0
	s_and_b64 s[4:5], s[46:47], vcc
	s_and_saveexec_b64 s[2:3], s[4:5]
	s_cbranch_execz .Lfb2_join
	v_mov_b32_e32 v0, 0x24400
	ds_read_b32 v1, v0
	ds_read_b32 v2, v0 offset:4
	ds_read_b32 v3, v0 offset:8
	s_waitcnt lgkmcnt(0)
	v_readfirstlane_b32 s4, v1
	v_readfirstlane_b32 s5, v2
	v_readfirstlane_b32 s6, v3
	s_add_u32 s7, s6, 1
	v_mov_b32_e32 v4, s7
	ds_write_b32 v0, v4 offset:8
	s_mul_i32 s8, s7, s4
	s_mul_i32 s9, s7, s5
	s_lshl_b32 s10, s23, 7
	s_add_u32 s10, s10, 0x3600
	v_mov_b32_e32 v1, s10
	v_mov_b32_e32 v2, 1
	global_atomic_add v3, v1, v2, s[40:41] sc0
	s_waitcnt vmcnt(0)
	v_readfirstlane_b32 s11, v3
	s_add_u32 s11, s11, 1
	v_mov_b32_e32 v1, 0x3e00
	s_cmp_lg_u32 s11, s8
	s_cbranch_scc1 .Lfb2_spin
	buffer_wbl2 sc1
	s_waitcnt vmcnt(0)
	global_atomic_add v1, v2, s[40:41]

.Lmq3k_done:
.LBB0_1140:
	s_cmp_lt_i32 s45, 5
	s_cbranch_scc1 .LBB0_1194
	s_waitcnt vmcnt(0) lgkmcnt(0)
	s_barrier
	v_mbcnt_hi_u32_b32 v0, -1, v210
	v_cmp_eq_u32_e32 vcc, 0, v0
	s_and_b64 s[4:5], s[46:47], vcc
	s_and_saveexec_b64 s[2:3], s[4:5]
	s_cbranch_execz .Lfb3_join
	v_mov_b32_e32 v0, 0x24400
	ds_read_b32 v1, v0
	ds_read_b32 v2, v0 offset:4
	ds_read_b32 v3, v0 offset:8
	s_waitcnt lgkmcnt(0)
	v_readfirstlane_b32 s4, v1
	v_readfirstlane_b32 s5, v2
	v_readfirstlane_b32 s6, v3
	s_add_u32 s7, s6, 1
	v_mov_b32_e32 v4, s7
	ds_write_b32 v0, v4 offset:8
	s_mul_i32 s8, s7, s4
	s_mul_i32 s9, s7, s5
	s_lshl_b32 s10, s23, 7
	s_add_u32 s10, s10, 0x3600
	v_mov_b32_e32 v1, s10
	v_mov_b32_e32 v2, 1
	global_atomic_add v3, v1, v2, s[40:41] sc0
	s_waitcnt vmcnt(0)
	v_readfirstlane_b32 s11, v3
	s_add_u32 s11, s11, 1
	v_mov_b32_e32 v1, 0x3e00
	s_cmp_lg_u32 s11, s8
	s_cbranch_scc1 .Lfb3_spin
	buffer_wbl2 sc1
	s_waitcnt vmcnt(0)
	global_atomic_add v1, v2, s[40:41]

.LBB0_1213:
	s_setprio 0
	s_cmp_lt_i32 s45, 6
	s_cbranch_scc1 .LBB0_1267
	s_waitcnt vmcnt(0) lgkmcnt(0)
	s_barrier
	v_mbcnt_hi_u32_b32 v0, -1, v210
	v_cmp_eq_u32_e32 vcc, 0, v0
	s_and_b64 s[4:5], s[46:47], vcc
	s_and_saveexec_b64 s[2:3], s[4:5]
	s_cbranch_execz .Lfb4_join
	v_mov_b32_e32 v0, 0x24400
	ds_read_b32 v1, v0
	ds_read_b32 v2, v0 offset:4
	ds_read_b32 v3, v0 offset:8
	s_waitcnt lgkmcnt(0)
	v_readfirstlane_b32 s4, v1
	v_readfirstlane_b32 s5, v2
	v_readfirstlane_b32 s6, v3
	s_add_u32 s7, s6, 1
	v_mov_b32_e32 v4, s7
	ds_write_b32 v0, v4 offset:8
	s_mul_i32 s8, s7, s4
	s_mul_i32 s9, s7, s5
	s_lshl_b32 s10, s23, 7
	s_add_u32 s10, s10, 0x3600
	v_mov_b32_e32 v1, s10
	v_mov_b32_e32 v2, 1
	global_atomic_add v3, v1, v2, s[40:41] sc0
	s_waitcnt vmcnt(0)
	v_readfirstlane_b32 s11, v3
	s_add_u32 s11, s11, 1
	v_mov_b32_e32 v1, 0x3e00
	s_cmp_lg_u32 s11, s8
	s_cbranch_scc1 .Lfb4_spin
	buffer_wbl2 sc1
	s_waitcnt vmcnt(0)
	global_atomic_add v1, v2, s[40:41]

.LBB0_1343:
	s_cmp_lt_i32 s45, 7
	s_cbranch_scc1 .LBB0_1397
	s_waitcnt vmcnt(0) lgkmcnt(0)
	s_barrier
	v_mbcnt_hi_u32_b32 v0, -1, v210
	v_cmp_eq_u32_e32 vcc, 0, v0
	s_and_b64 s[4:5], s[46:47], vcc
	s_and_saveexec_b64 s[2:3], s[4:5]
	s_cbranch_execz .Lfb5_join
	v_mov_b32_e32 v0, 0x24400
	ds_read_b32 v1, v0
	ds_read_b32 v2, v0 offset:4
	ds_read_b32 v3, v0 offset:8
	s_waitcnt lgkmcnt(0)
	v_readfirstlane_b32 s4, v1
	v_readfirstlane_b32 s5, v2
	v_readfirstlane_b32 s6, v3
	s_add_u32 s7, s6, 1
	v_mov_b32_e32 v4, s7
	ds_write_b32 v0, v4 offset:8
	s_mul_i32 s8, s7, s4
	s_mul_i32 s9, s7, s5
	s_lshl_b32 s10, s23, 7
	s_add_u32 s10, s10, 0x3600
	v_mov_b32_e32 v1, s10
	v_mov_b32_e32 v2, 1
	global_atomic_add v3, v1, v2, s[40:41] sc0
	s_waitcnt vmcnt(0)
	v_readfirstlane_b32 s11, v3
	s_add_u32 s11, s11, 1
	v_mov_b32_e32 v1, 0x3e00
	s_cmp_lg_u32 s11, s8
	s_cbranch_scc1 .Lfb5_spin
	buffer_wbl2 sc1
	s_waitcnt vmcnt(0)
	global_atomic_add v1, v2, s[40:41]

.LBB0_1403:
	s_or_b64 exec, exec, s[4:5]
	s_cmp_lt_i32 s45, 8
	s_cbranch_scc1 .LBB0_1457
	s_waitcnt vmcnt(0) lgkmcnt(0)
	s_barrier
	v_mbcnt_hi_u32_b32 v0, -1, v210
	v_cmp_eq_u32_e32 vcc, 0, v0
	s_and_b64 s[4:5], s[46:47], vcc
	s_and_saveexec_b64 s[2:3], s[4:5]
	s_cbranch_execz .Lfb6_join
	v_mov_b32_e32 v0, 0x24400
	ds_read_b32 v1, v0
	ds_read_b32 v2, v0 offset:4
	ds_read_b32 v3, v0 offset:8
	s_waitcnt lgkmcnt(0)
	v_readfirstlane_b32 s4, v1
	v_readfirstlane_b32 s5, v2
	v_readfirstlane_b32 s6, v3
	s_add_u32 s7, s6, 1
	v_mov_b32_e32 v4, s7
	ds_write_b32 v0, v4 offset:8
	s_mul_i32 s8, s7, s4
	s_mul_i32 s9, s7, s5
	s_lshl_b32 s10, s23, 7
	s_add_u32 s10, s10, 0x3600
	v_mov_b32_e32 v1, s10
	v_mov_b32_e32 v2, 1
	global_atomic_add v3, v1, v2, s[40:41] sc0
	s_waitcnt vmcnt(0)
	v_readfirstlane_b32 s11, v3
	s_add_u32 s11, s11, 1
	v_mov_b32_e32 v1, 0x3e00
	s_cmp_lg_u32 s11, s8
	s_cbranch_scc1 .Lfb6_spin
	buffer_wbl2 sc1
	s_waitcnt vmcnt(0)
	global_atomic_add v1, v2, s[40:41]

.LBB0_2077:
	s_cmp_lt_i32 s45, 9
	s_cbranch_scc1 .LBB0_2131
	s_waitcnt vmcnt(0) lgkmcnt(0)
	s_barrier
	v_mbcnt_hi_u32_b32 v0, -1, v210
	v_cmp_eq_u32_e32 vcc, 0, v0
	s_and_b64 s[4:5], s[46:47], vcc
	s_and_saveexec_b64 s[2:3], s[4:5]
	s_cbranch_execz .Lfb7_join
	v_mov_b32_e32 v0, 0x24400
	ds_read_b32 v1, v0
	ds_read_b32 v2, v0 offset:4
	ds_read_b32 v3, v0 offset:8
	s_waitcnt lgkmcnt(0)
	v_readfirstlane_b32 s4, v1
	v_readfirstlane_b32 s5, v2
	v_readfirstlane_b32 s6, v3
	s_add_u32 s7, s6, 1
	v_mov_b32_e32 v4, s7
	ds_write_b32 v0, v4 offset:8
	s_mul_i32 s8, s7, s4
	s_mul_i32 s9, s7, s5
	s_lshl_b32 s10, s23, 7
	s_add_u32 s10, s10, 0x3600
	v_mov_b32_e32 v1, s10
	v_mov_b32_e32 v2, 1
	global_atomic_add v3, v1, v2, s[40:41] sc0
	s_waitcnt vmcnt(0)
	v_readfirstlane_b32 s11, v3
	s_add_u32 s11, s11, 1
	v_mov_b32_e32 v1, 0x3e00
	s_cmp_lg_u32 s11, s8
	s_cbranch_scc1 .Lfb7_spin
	buffer_wbl2 sc1
	s_waitcnt vmcnt(0)
	global_atomic_add v1, v2, s[40:41]

.LBB0_2157:
	s_setprio 0
	s_cmp_lt_i32 s45, 10
	s_cbranch_scc1 .LBB0_2211
	s_waitcnt vmcnt(0) lgkmcnt(0)
	s_barrier
	v_mbcnt_hi_u32_b32 v0, -1, v210
	v_cmp_eq_u32_e32 vcc, 0, v0
	s_and_b64 s[4:5], s[46:47], vcc
	s_and_saveexec_b64 s[2:3], s[4:5]
	s_cbranch_execz .Lfb8_join
	v_mov_b32_e32 v0, 0x24400
	ds_read_b32 v1, v0
	ds_read_b32 v2, v0 offset:4
	ds_read_b32 v3, v0 offset:8
	s_waitcnt lgkmcnt(0)
	v_readfirstlane_b32 s4, v1
	v_readfirstlane_b32 s5, v2
	v_readfirstlane_b32 s6, v3
	s_add_u32 s7, s6, 1
	v_mov_b32_e32 v4, s7
	ds_write_b32 v0, v4 offset:8
	s_mul_i32 s8, s7, s4
	s_mul_i32 s9, s7, s5
	s_lshl_b32 s10, s23, 7
	s_add_u32 s10, s10, 0x3600
	v_mov_b32_e32 v1, s10
	v_mov_b32_e32 v2, 1
	global_atomic_add v3, v1, v2, s[40:41] sc0
	s_waitcnt vmcnt(0)
	v_readfirstlane_b32 s11, v3
	s_add_u32 s11, s11, 1
	v_mov_b32_e32 v1, 0x3e00
	s_cmp_lg_u32 s11, s8
	s_cbranch_scc1 .Lfb8_spin
	buffer_wbl2 sc1
	s_waitcnt vmcnt(0)
	global_atomic_add v1, v2, s[40:41]

.LBB0_2287:
	s_cmp_lt_i32 s45, 11
	s_cbranch_scc1 .LBB0_2341
	s_waitcnt vmcnt(0) lgkmcnt(0)
	s_barrier
	v_mbcnt_hi_u32_b32 v0, -1, v210
	v_cmp_eq_u32_e32 vcc, 0, v0
	s_and_b64 s[4:5], s[46:47], vcc
	s_and_saveexec_b64 s[2:3], s[4:5]
	s_cbranch_execz .Lfb9_join
	v_mov_b32_e32 v0, 0x24400
	ds_read_b32 v1, v0
	ds_read_b32 v2, v0 offset:4
	ds_read_b32 v3, v0 offset:8
	s_waitcnt lgkmcnt(0)
	v_readfirstlane_b32 s4, v1
	v_readfirstlane_b32 s5, v2
	v_readfirstlane_b32 s6, v3
	s_add_u32 s7, s6, 1
	v_mov_b32_e32 v4, s7
	ds_write_b32 v0, v4 offset:8
	s_mul_i32 s8, s7, s4
	s_mul_i32 s9, s7, s5
	s_lshl_b32 s10, s23, 7
	s_add_u32 s10, s10, 0x3600
	v_mov_b32_e32 v1, s10
	v_mov_b32_e32 v2, 1
	global_atomic_add v3, v1, v2, s[40:41] sc0
	s_waitcnt vmcnt(0)
	v_readfirstlane_b32 s11, v3
	s_add_u32 s11, s11, 1
	v_mov_b32_e32 v1, 0x3e00
	s_cmp_lg_u32 s11, s8
	s_cbranch_scc1 .Lfb9_spin
	buffer_wbl2 sc1
	s_waitcnt vmcnt(0)
	global_atomic_add v1, v2, s[40:41]

.LBB0_2347:
	s_or_b64 exec, exec, s[4:5]
	s_cmp_lt_i32 s45, 12
	s_cbranch_scc1 .LBB0_2401
	s_waitcnt vmcnt(0) lgkmcnt(0)
	s_barrier
	v_mbcnt_hi_u32_b32 v0, -1, v210
	v_cmp_eq_u32_e32 vcc, 0, v0
	s_and_b64 s[4:5], s[46:47], vcc
	s_and_saveexec_b64 s[2:3], s[4:5]
	s_cbranch_execz .Lfb10_join
	v_mov_b32_e32 v0, 0x24400
	ds_read_b32 v1, v0
	ds_read_b32 v2, v0 offset:4
	ds_read_b32 v3, v0 offset:8
	s_waitcnt lgkmcnt(0)
	v_readfirstlane_b32 s4, v1
	v_readfirstlane_b32 s5, v2
	v_readfirstlane_b32 s6, v3
	s_add_u32 s7, s6, 1
	v_mov_b32_e32 v4, s7
	ds_write_b32 v0, v4 offset:8
	s_mul_i32 s8, s7, s4
	s_mul_i32 s9, s7, s5
	s_lshl_b32 s10, s23, 7
	s_add_u32 s10, s10, 0x3600
	v_mov_b32_e32 v1, s10
	v_mov_b32_e32 v2, 1
	global_atomic_add v3, v1, v2, s[40:41] sc0
	s_waitcnt vmcnt(0)
	v_readfirstlane_b32 s11, v3
	s_add_u32 s11, s11, 1
	v_mov_b32_e32 v1, 0x3e00
	s_cmp_lg_u32 s11, s8
	s_cbranch_scc1 .Lfb10_spin
	buffer_wbl2 sc1
	s_waitcnt vmcnt(0)
	global_atomic_add v1, v2, s[40:41]

.LBB0_3853:
	s_cmp_lt_i32 s45, 13
	s_cbranch_scc1 .LBB0_3907
	s_waitcnt vmcnt(0) lgkmcnt(0)
	s_barrier
	v_mbcnt_hi_u32_b32 v0, -1, v210
	v_cmp_eq_u32_e32 vcc, 0, v0
	s_and_b64 s[4:5], s[46:47], vcc
	s_and_saveexec_b64 s[2:3], s[4:5]
	s_cbranch_execz .Lfb11_join
	v_mov_b32_e32 v0, 0x24400
	ds_read_b32 v1, v0
	ds_read_b32 v2, v0 offset:4
	ds_read_b32 v3, v0 offset:8
	s_waitcnt lgkmcnt(0)
	v_readfirstlane_b32 s4, v1
	v_readfirstlane_b32 s5, v2
	v_readfirstlane_b32 s6, v3
	s_add_u32 s7, s6, 1
	v_mov_b32_e32 v4, s7
	ds_write_b32 v0, v4 offset:8
	s_mul_i32 s8, s7, s4
	s_mul_i32 s9, s7, s5
	s_lshl_b32 s10, s23, 7
	s_add_u32 s10, s10, 0x3600
	v_mov_b32_e32 v1, s10
	v_mov_b32_e32 v2, 1
	global_atomic_add v3, v1, v2, s[40:41] sc0
	s_waitcnt vmcnt(0)
	v_readfirstlane_b32 s11, v3
	s_add_u32 s11, s11, 1
	v_mov_b32_e32 v1, 0x3e00
	s_cmp_lg_u32 s11, s8
	s_cbranch_scc1 .Lfb11_spin
	buffer_wbl2 sc1
	s_waitcnt vmcnt(0)
	global_atomic_add v1, v2, s[40:41]

.LBB0_4084:
	s_cmp_lt_i32 s45, 14
	s_cbranch_scc1 .LBB0_4138
	s_waitcnt vmcnt(0) lgkmcnt(0)
	s_barrier
	v_mbcnt_hi_u32_b32 v0, -1, v210
	v_cmp_eq_u32_e32 vcc, 0, v0
	s_and_b64 s[4:5], s[46:47], vcc
	s_and_saveexec_b64 s[2:3], s[4:5]
	s_cbranch_execz .Lfb12_join
	v_mov_b32_e32 v0, 0x24400
	ds_read_b32 v1, v0
	ds_read_b32 v2, v0 offset:4
	ds_read_b32 v3, v0 offset:8
	s_waitcnt lgkmcnt(0)
	v_readfirstlane_b32 s4, v1
	v_readfirstlane_b32 s5, v2
	v_readfirstlane_b32 s6, v3
	s_add_u32 s7, s6, 1
	v_mov_b32_e32 v4, s7
	ds_write_b32 v0, v4 offset:8
	s_mul_i32 s8, s7, s4
	s_mul_i32 s9, s7, s5
	s_lshl_b32 s10, s23, 7
	s_add_u32 s10, s10, 0x3600
	v_mov_b32_e32 v1, s10
	v_mov_b32_e32 v2, 1
	global_atomic_add v3, v1, v2, s[40:41] sc0
	s_waitcnt vmcnt(0)
	v_readfirstlane_b32 s11, v3
	s_add_u32 s11, s11, 1
	v_mov_b32_e32 v1, 0x3e00
	s_cmp_lg_u32 s11, s8
	s_cbranch_scc1 .Lfb12_spin
	buffer_wbl2 sc1
	s_waitcnt vmcnt(0)
	global_atomic_add v1, v2, s[40:41]

.LBB0_4162:
	s_cmp_lt_i32 s45, 15
	s_cbranch_scc1 .LBB0_4216
	s_waitcnt vmcnt(0) lgkmcnt(0)
	s_barrier
	v_mbcnt_hi_u32_b32 v0, -1, v210
	v_cmp_eq_u32_e32 vcc, 0, v0
	s_and_b64 s[4:5], s[46:47], vcc
	s_and_saveexec_b64 s[2:3], s[4:5]
	s_cbranch_execz .Lfb13_join
	v_mov_b32_e32 v0, 0x24400
	ds_read_b32 v1, v0
	ds_read_b32 v2, v0 offset:4
	ds_read_b32 v3, v0 offset:8
	s_waitcnt lgkmcnt(0)
	v_readfirstlane_b32 s4, v1
	v_readfirstlane_b32 s5, v2
	v_readfirstlane_b32 s6, v3
	s_add_u32 s7, s6, 1
	v_mov_b32_e32 v4, s7
	ds_write_b32 v0, v4 offset:8
	s_mul_i32 s8, s7, s4
	s_mul_i32 s9, s7, s5
	s_lshl_b32 s10, s23, 7
	s_add_u32 s10, s10, 0x3600
	v_mov_b32_e32 v1, s10
	v_mov_b32_e32 v2, 1
	global_atomic_add v3, v1, v2, s[40:41] sc0
	s_waitcnt vmcnt(0)
	v_readfirstlane_b32 s11, v3
	s_add_u32 s11, s11, 1
	v_mov_b32_e32 v1, 0x3e00
	s_cmp_lg_u32 s11, s8
	s_cbranch_scc1 .Lfb13_spin
	buffer_wbl2 sc1
	s_waitcnt vmcnt(0)
	global_atomic_add v1, v2, s[40:41]

.LBB0_4307:
	s_cmp_lt_i32 s45, 16
	s_cbranch_scc1 .LBB0_4361
	s_waitcnt vmcnt(0) lgkmcnt(0)
	s_barrier
	v_mbcnt_hi_u32_b32 v0, -1, v210
	v_cmp_eq_u32_e32 vcc, 0, v0
	s_and_b64 s[4:5], s[46:47], vcc
	s_and_saveexec_b64 s[2:3], s[4:5]
	s_cbranch_execz .Lfb14_join
	v_mov_b32_e32 v0, 0x24400
	ds_read_b32 v1, v0
	ds_read_b32 v2, v0 offset:4
	ds_read_b32 v3, v0 offset:8
	s_waitcnt lgkmcnt(0)
	v_readfirstlane_b32 s4, v1
	v_readfirstlane_b32 s5, v2
	v_readfirstlane_b32 s6, v3
	s_add_u32 s7, s6, 1
	v_mov_b32_e32 v4, s7
	ds_write_b32 v0, v4 offset:8
	s_mul_i32 s8, s7, s4
	s_mul_i32 s9, s7, s5
	s_lshl_b32 s10, s23, 7
	s_add_u32 s10, s10, 0x3600
	v_mov_b32_e32 v1, s10
	v_mov_b32_e32 v2, 1
	global_atomic_add v3, v1, v2, s[40:41] sc0
	s_waitcnt vmcnt(0)
	v_readfirstlane_b32 s11, v3
	s_add_u32 s11, s11, 1
	v_mov_b32_e32 v1, 0x3e00
	s_cmp_lg_u32 s11, s8
	s_cbranch_scc1 .Lfb14_spin
	buffer_wbl2 sc1
	s_waitcnt vmcnt(0)
	global_atomic_add v1, v2, s[40:41]

.LBB0_4416:
	s_setprio 0
	s_cmp_lt_i32 s45, 17
	s_cbranch_scc1 .LBB0_4470
	s_waitcnt vmcnt(0) lgkmcnt(0)
	s_barrier
	v_mbcnt_hi_u32_b32 v0, -1, v210
	v_cmp_eq_u32_e32 vcc, 0, v0
	s_and_b64 s[4:5], s[46:47], vcc
	s_and_saveexec_b64 s[2:3], s[4:5]
	s_cbranch_execz .Lfb15_join
	v_mov_b32_e32 v0, 0x24400
	ds_read_b32 v1, v0
	ds_read_b32 v2, v0 offset:4
	ds_read_b32 v3, v0 offset:8
	s_waitcnt lgkmcnt(0)
	v_readfirstlane_b32 s4, v1
	v_readfirstlane_b32 s5, v2
	v_readfirstlane_b32 s6, v3
	s_add_u32 s7, s6, 1
	v_mov_b32_e32 v4, s7
	ds_write_b32 v0, v4 offset:8
	s_mul_i32 s8, s7, s4
	s_mul_i32 s9, s7, s5
	s_lshl_b32 s10, s23, 7
	s_add_u32 s10, s10, 0x3600
	v_mov_b32_e32 v1, s10
	v_mov_b32_e32 v2, 1
	global_atomic_add v3, v1, v2, s[40:41] sc0
	s_waitcnt vmcnt(0)
	v_readfirstlane_b32 s11, v3
	s_add_u32 s11, s11, 1
	v_mov_b32_e32 v1, 0x3e00
	s_cmp_lg_u32 s11, s8
	s_cbranch_scc1 .Lfb15_spin
	buffer_wbl2 sc1
	s_waitcnt vmcnt(0)
	global_atomic_add v1, v2, s[40:41]

.LBB0_4546:
	s_cmp_lt_i32 s45, 18
	s_cbranch_scc1 .LBB0_4600
	s_waitcnt vmcnt(0) lgkmcnt(0)
	s_barrier
	v_mbcnt_hi_u32_b32 v0, -1, v210
	v_cmp_eq_u32_e32 vcc, 0, v0
	s_and_b64 s[4:5], s[46:47], vcc
	s_and_saveexec_b64 s[2:3], s[4:5]
	s_cbranch_execz .Lfb16_join
	v_mov_b32_e32 v0, 0x24400
	ds_read_b32 v1, v0
	ds_read_b32 v2, v0 offset:4
	ds_read_b32 v3, v0 offset:8
	s_waitcnt lgkmcnt(0)
	v_readfirstlane_b32 s4, v1
	v_readfirstlane_b32 s5, v2
	v_readfirstlane_b32 s6, v3
	s_add_u32 s7, s6, 1
	v_mov_b32_e32 v4, s7
	ds_write_b32 v0, v4 offset:8
	s_mul_i32 s8, s7, s4
	s_mul_i32 s9, s7, s5
	s_lshl_b32 s10, s23, 7
	s_add_u32 s10, s10, 0x3600
	v_mov_b32_e32 v1, s10
	v_mov_b32_e32 v2, 1
	global_atomic_add v3, v1, v2, s[40:41] sc0
	s_waitcnt vmcnt(0)
	v_readfirstlane_b32 s11, v3
	s_add_u32 s11, s11, 1
	v_mov_b32_e32 v1, 0x3e00
	s_cmp_lg_u32 s11, s8
	s_cbranch_scc1 .Lfb16_spin
	buffer_wbl2 sc1
	s_waitcnt vmcnt(0)
	global_atomic_add v1, v2, s[40:41]

.LBB0_4606:
	s_or_b64 exec, exec, s[4:5]
	s_cmp_lt_i32 s45, 19
	s_cbranch_scc1 .LBB0_4660
	s_waitcnt vmcnt(0) lgkmcnt(0)
	s_barrier
	v_mbcnt_hi_u32_b32 v0, -1, v210
	v_cmp_eq_u32_e32 vcc, 0, v0
	s_and_b64 s[4:5], s[46:47], vcc
	s_and_saveexec_b64 s[2:3], s[4:5]
	s_cbranch_execz .Lfb17_join
	v_mov_b32_e32 v0, 0x24400
	ds_read_b32 v1, v0
	ds_read_b32 v2, v0 offset:4
	ds_read_b32 v3, v0 offset:8
	s_waitcnt lgkmcnt(0)
	v_readfirstlane_b32 s4, v1
	v_readfirstlane_b32 s5, v2
	v_readfirstlane_b32 s6, v3
	s_add_u32 s7, s6, 1
	v_mov_b32_e32 v4, s7
	ds_write_b32 v0, v4 offset:8
	s_mul_i32 s8, s7, s4
	s_mul_i32 s9, s7, s5
	s_lshl_b32 s10, s23, 7
	s_add_u32 s10, s10, 0x3600
	v_mov_b32_e32 v1, s10
	v_mov_b32_e32 v2, 1
	global_atomic_add v3, v1, v2, s[40:41] sc0
	s_waitcnt vmcnt(0)
	v_readfirstlane_b32 s11, v3
	s_add_u32 s11, s11, 1
	v_mov_b32_e32 v1, 0x3e00
	s_cmp_lg_u32 s11, s8
	s_cbranch_scc1 .Lfb17_spin
	buffer_wbl2 sc1
	s_waitcnt vmcnt(0)
	global_atomic_add v1, v2, s[40:41]

.LBB0_5176:
	s_cmp_lt_i32 s45, 20
	s_cbranch_scc1 .LBB0_5230
	s_waitcnt vmcnt(0) lgkmcnt(0)
	s_barrier
	v_mbcnt_hi_u32_b32 v0, -1, v210
	v_cmp_eq_u32_e32 vcc, 0, v0
	s_and_b64 s[4:5], s[46:47], vcc
	s_and_saveexec_b64 s[2:3], s[4:5]
	s_cbranch_execz .Lfb18_join
	v_mov_b32_e32 v0, 0x24400
	ds_read_b32 v1, v0
	ds_read_b32 v2, v0 offset:4
	ds_read_b32 v3, v0 offset:8
	s_waitcnt lgkmcnt(0)
	v_readfirstlane_b32 s4, v1
	v_readfirstlane_b32 s5, v2
	v_readfirstlane_b32 s6, v3
	s_add_u32 s7, s6, 1
	v_mov_b32_e32 v4, s7
	ds_write_b32 v0, v4 offset:8
	s_mul_i32 s8, s7, s4
	s_mul_i32 s9, s7, s5
	s_lshl_b32 s10, s23, 7
	s_add_u32 s10, s10, 0x3600
	v_mov_b32_e32 v1, s10
	v_mov_b32_e32 v2, 1
	global_atomic_add v3, v1, v2, s[40:41] sc0
	s_waitcnt vmcnt(0)
	v_readfirstlane_b32 s11, v3
	s_add_u32 s11, s11, 1
	v_mov_b32_e32 v1, 0x3e00
	s_cmp_lg_u32 s11, s8
	s_cbranch_scc1 .Lfb18_spin
	buffer_wbl2 sc1
	s_waitcnt vmcnt(0)
	global_atomic_add v1, v2, s[40:41]

.Lmq19k_done:
.LBB0_5505:
	s_cmp_lt_i32 s45, 21
	s_cbranch_scc1 .LBB0_5559
	s_waitcnt vmcnt(0) lgkmcnt(0)
	s_barrier
	v_mbcnt_hi_u32_b32 v0, -1, v210
	v_cmp_eq_u32_e32 vcc, 0, v0
	s_and_b64 s[4:5], s[46:47], vcc
	s_and_saveexec_b64 s[2:3], s[4:5]
	s_cbranch_execz .Lfb19_join
	v_mov_b32_e32 v0, 0x24400
	ds_read_b32 v1, v0
	ds_read_b32 v2, v0 offset:4
	ds_read_b32 v3, v0 offset:8
	s_waitcnt lgkmcnt(0)
	v_readfirstlane_b32 s4, v1
	v_readfirstlane_b32 s5, v2
	v_readfirstlane_b32 s6, v3
	s_add_u32 s7, s6, 1
	v_mov_b32_e32 v4, s7
	ds_write_b32 v0, v4 offset:8
	s_mul_i32 s8, s7, s4
	s_mul_i32 s9, s7, s5
	s_lshl_b32 s10, s23, 7
	s_add_u32 s10, s10, 0x3600
	v_mov_b32_e32 v1, s10
	v_mov_b32_e32 v2, 1
	global_atomic_add v3, v1, v2, s[40:41] sc0
	s_waitcnt vmcnt(0)
	v_readfirstlane_b32 s11, v3
	s_add_u32 s11, s11, 1
	v_mov_b32_e32 v1, 0x3e00
	s_cmp_lg_u32 s11, s8
	s_cbranch_scc1 .Lfb19_spin
	buffer_wbl2 sc1
	s_waitcnt vmcnt(0)
	global_atomic_add v1, v2, s[40:41]

.LBB0_5578:
	s_setprio 0
	s_cmp_lt_i32 s45, 22
	s_cbranch_scc1 .LBB0_5632
	s_waitcnt vmcnt(0) lgkmcnt(0)
	s_barrier
	v_mbcnt_hi_u32_b32 v0, -1, v210
	v_cmp_eq_u32_e32 vcc, 0, v0
	s_and_b64 s[4:5], s[46:47], vcc
	s_and_saveexec_b64 s[2:3], s[4:5]
	s_cbranch_execz .Lfb20_join
	v_mov_b32_e32 v0, 0x24400
	ds_read_b32 v1, v0
	ds_read_b32 v2, v0 offset:4
	ds_read_b32 v3, v0 offset:8
	s_waitcnt lgkmcnt(0)
	v_readfirstlane_b32 s4, v1
	v_readfirstlane_b32 s5, v2
	v_readfirstlane_b32 s6, v3
	s_add_u32 s7, s6, 1
	v_mov_b32_e32 v4, s7
	ds_write_b32 v0, v4 offset:8
	s_mul_i32 s8, s7, s4
	s_mul_i32 s9, s7, s5
	s_lshl_b32 s10, s23, 7
	s_add_u32 s10, s10, 0x3600
	v_mov_b32_e32 v1, s10
	v_mov_b32_e32 v2, 1
	global_atomic_add v3, v1, v2, s[40:41] sc0
	s_waitcnt vmcnt(0)
	v_readfirstlane_b32 s11, v3
	s_add_u32 s11, s11, 1
	v_mov_b32_e32 v1, 0x3e00
	s_cmp_lg_u32 s11, s8
	s_cbranch_scc1 .Lfb20_spin
	buffer_wbl2 sc1
	s_waitcnt vmcnt(0)
	global_atomic_add v1, v2, s[40:41]

.LBB0_5708:
	s_cmp_lt_i32 s45, 23
	s_cbranch_scc1 .LBB0_5762
	s_waitcnt vmcnt(0) lgkmcnt(0)
	s_barrier
	v_mbcnt_hi_u32_b32 v0, -1, v210
	v_cmp_eq_u32_e32 vcc, 0, v0
	s_and_b64 s[4:5], s[46:47], vcc
	s_and_saveexec_b64 s[2:3], s[4:5]
	s_cbranch_execz .Lfb21_join
	v_mov_b32_e32 v0, 0x24400
	ds_read_b32 v1, v0
	ds_read_b32 v2, v0 offset:4
	ds_read_b32 v3, v0 offset:8
	s_waitcnt lgkmcnt(0)
	v_readfirstlane_b32 s4, v1
	v_readfirstlane_b32 s5, v2
	v_readfirstlane_b32 s6, v3
	s_add_u32 s7, s6, 1
	v_mov_b32_e32 v4, s7
	ds_write_b32 v0, v4 offset:8
	s_mul_i32 s8, s7, s4
	s_mul_i32 s9, s7, s5
	s_lshl_b32 s10, s23, 7
	s_add_u32 s10, s10, 0x3600
	v_mov_b32_e32 v1, s10
	v_mov_b32_e32 v2, 1
	global_atomic_add v3, v1, v2, s[40:41] sc0
	s_waitcnt vmcnt(0)
	v_readfirstlane_b32 s11, v3
	s_add_u32 s11, s11, 1
	v_mov_b32_e32 v1, 0x3e00
	s_cmp_lg_u32 s11, s8
	s_cbranch_scc1 .Lfb21_spin
	buffer_wbl2 sc1
	s_waitcnt vmcnt(0)
	global_atomic_add v1, v2, s[40:41]
